# P2c: the two rows a wave keeps in flight are adjacent (2*gw + i*2*NGW, +1) instead of NGW apart, so previous-row slices are shared instead of re-fetched
# baseline (speedup 1.0000x reference)
.LBB0_908:
	s_or_b64 exec, exec, s[0:1]
	v_readlane_b32 s0, v249, 12
	v_readlane_b32 s1, v249, 13
	s_andn2_b64 vcc, exec, s[0:1]
	s_waitcnt lgkmcnt(0)
	v_cndmask_b32_e64 v0, 0, 1, s[0:1]
	v_cmp_ne_u32_e64 s[2:3], 1, v0
	s_barrier
	s_nop 0
	v_writelane_b32 v249, s2, 56
	s_nop 1
	v_writelane_b32 v249, s3, 57
	s_cbranch_vccnz .LBB0_943
	s_lshl_b32 s98, s70, 1
	v_readlane_b32 s0, v249, 23
	v_mov_b32_e32 v177, 0
	v_readlane_b32 s1, v249, 24
	v_lshlrev_b32_e32 v0, 5, v158
	v_mov_b32_e32 v1, v177
	v_lshl_add_u64 v[118:119], s[0:1], 0, v[176:177]
	v_readlane_b32 s0, v250, 7
	v_readlane_b32 s8, v250, 15
	v_readlane_b32 s9, v250, 16
	v_readlane_b32 s10, v250, 17
	v_readlane_b32 s11, v250, 18
	v_readlane_b32 s12, v250, 19
	v_readlane_b32 s13, v250, 20
	v_readlane_b32 s14, v250, 21
	v_readlane_b32 s15, v250, 22
	v_readlane_b32 s8, v250, 23
	v_readlane_b32 s1, v250, 8
	v_readlane_b32 s9, v250, 24
	v_readlane_b32 s14, v250, 29
	v_readlane_b32 s15, v250, 30
	v_readlane_b32 s22, v250, 37
	v_readlane_b32 s23, v250, 38
	v_readlane_b32 s2, v250, 9
	v_readlane_b32 s3, v250, 10
	v_readlane_b32 s4, v250, 11
	v_readlane_b32 s5, v250, 12
	v_readlane_b32 s6, v250, 13
	v_readlane_b32 s7, v250, 14
	v_readlane_b32 s10, v250, 25
	v_readlane_b32 s11, v250, 26
	v_readlane_b32 s12, v250, 27
	v_readlane_b32 s13, v250, 28
	s_mov_b64 s[0:1], s[8:9]
	s_mov_b64 s[14:15], s[22:23]
	v_or_b32_e32 v2, 0x1000, v0
	v_mov_b32_e32 v3, v177
	v_lshl_add_u64 v[120:121], s[4:5], 0, v[0:1]
	v_lshl_add_u64 v[122:123], s[0:1], 0, v[0:1]
	v_lshl_add_u64 v[124:125], s[4:5], 0, v[2:3]
	v_lshl_add_u64 v[126:127], s[0:1], 0, v[2:3]
	v_lshl_add_u64 v[128:129], s[14:15], 0, v[0:1]
	v_readlane_b32 s0, v250, 44
	v_readlane_b32 s1, v250, 45
	v_readlane_b32 s2, v250, 46
	v_readlane_b32 s3, v250, 47
	v_readlane_b32 s4, v250, 48
	v_readlane_b32 s5, v250, 49
	v_readlane_b32 s16, v250, 31
	v_readlane_b32 s17, v250, 32
	v_readlane_b32 s18, v250, 33
	v_readlane_b32 s19, v250, 34
	v_readlane_b32 s6, v250, 50
	v_readlane_b32 s7, v250, 51
	v_readlane_b32 s8, v250, 52
	v_readlane_b32 s9, v250, 53
	v_readlane_b32 s10, v250, 54
	v_readlane_b32 s11, v250, 55
	v_readlane_b32 s12, v250, 56
	v_readlane_b32 s13, v250, 57
	v_readlane_b32 s14, v250, 58
	v_readlane_b32 s15, v250, 59
	v_lshl_add_u64 v[130:131], s[0:1], 0, v[0:1]
	v_lshl_add_u64 v[132:133], s[2:3], 0, v[0:1]
	v_lshl_add_u64 v[134:135], s[4:5], 0, v[0:1]
	v_and_b32_e32 v0, 0x1e0, v0
	v_readlane_b32 s0, v249, 16
	v_lshl_add_u64 v[136:137], s[10:11], 0, v[0:1]
	v_readlane_b32 s1, v249, 17
	v_readlane_b32 s4, v250, 60
	v_readlane_b32 s12, v249, 4
	v_lshl_add_u64 v[138:139], s[0:1], 0, v[176:177]
	s_add_i32 s0, s98, 1
	v_readlane_b32 s13, v249, 5
	v_readlane_b32 s14, v249, 6
	v_readlane_b32 s15, v249, 7
	v_readlane_b32 s16, v249, 8
	v_readlane_b32 s17, v249, 9
	s_ashr_i32 s1, s0, 31
	v_readlane_b32 s18, v249, 10
	v_readlane_b32 s19, v249, 11
	s_mov_b64 s[12:13], s[16:17]
	s_add_i32 s24, s98, 0xffffc000
	s_lshl_b64 s[0:1], s[0:1], 10
	s_mov_b64 s[14:15], s[18:19]
	s_add_u32 s0, s14, s0
	v_readlane_b32 s10, v249, 2
	v_readlane_b32 s11, v249, 3
	s_addc_u32 s1, s15, s1
	s_ashr_i32 s73, s72, 31
	s_ashr_i32 s71, s70, 31
	s_lshl_b64 s[10:11], s[72:73], 10
	s_ashr_i32 s99, s98, 31
	s_lshl_b64 s[2:3], s[98:99], 10
	v_readlane_b32 s7, v250, 63
	s_add_u32 s12, s14, s2
	v_readlane_b32 s6, v250, 62
	s_addc_u32 s13, s15, s3
	s_mul_i32 s7, s98, 0xe00
	s_mul_hi_i32 s6, s98, 0xe00
	s_add_u32 s14, s92, s7
	s_addc_u32 s15, s93, s6
	s_add_u32 s2, s92, s2
	s_addc_u32 s3, s93, s3
	v_readlane_b32 s20, v250, 35
	v_readlane_b32 s21, v250, 36
	s_add_u32 s16, s2, 0xdf00000
	v_lshl_add_u64 v[112:113], s[62:63], 0, v[176:177]
	v_lshl_add_u64 v[114:115], s[86:87], 0, v[176:177]
	v_lshl_add_u64 v[116:117], s[90:91], 0, v[176:177]
	s_mul_hi_i32 s25, s72, 0xe00
	s_mul_i32 s26, s72, 0xe00
	s_addc_u32 s17, s3, 0
	s_mov_b64 s[18:19], 0x3300000
	v_mov_b32_e32 v152, 0xe00
	s_mov_b32 s27, 0x5f00000
	v_lshlrev_b32_e32 v140, 1, v178
	v_mov_b32_e32 v141, v177
	s_mov_b64 s[20:21], 0x2200000
	s_mov_b32 s28, 0x2200000
	v_mov_b32_e32 v153, 0x3a27c5ac
	s_mov_b32 s29, 0x800000
	v_mov_b32_e32 v154, 0x358637bd
	v_mov_b32_e32 v155, 0x1c00
	v_readlane_b32 s5, v250, 61
	v_readlane_b32 s8, v249, 0
	v_readlane_b32 s9, v249, 1
	s_branch .LBB0_912

.LBB0_912:
	v_lshl_add_u64 v[142:143], s[12:13], 0, v[176:177]
	v_add_co_u32_e32 v0, vcc, 0x3300000, v142
	s_add_i32 s22, s24, 0x4000
	s_nop 0
	v_addc_co_u32_e32 v1, vcc, 0, v143, vcc
	global_load_dwordx4 v[44:47], v[0:1], off
	v_lshl_add_u64 v[0:1], s[14:15], 0, v[176:177]
	v_add_co_u32_e32 v2, vcc, 0x2300000, v0
	s_max_i32 s2, s22, 1
	s_nop 0
	v_addc_co_u32_e32 v3, vcc, 0, v1, vcc
	s_add_i32 s2, s2, -1
	global_load_dwordx4 v[60:63], v[2:3], off
	global_load_dwordx4 v[68:71], v[2:3], off offset:1024
	global_load_dwordx4 v[52:55], v[2:3], off offset:2048
	v_add_co_u32_e32 v2, vcc, 0x1100000, v142
	v_mad_u64_u32 v[72:73], s[2:3], s2, v152, v[138:139]
	s_nop 0
	v_addc_co_u32_e32 v3, vcc, 0, v143, vcc
	global_load_dwordx4 v[88:91], v[72:73], off offset:1024
	global_load_dwordx4 v[92:95], v[72:73], off offset:2048
	global_load_dwordx4 v[64:67], v[2:3], off
	v_add_co_u32_e32 v2, vcc, s28, v142
	s_add_i32 s30, s24, 1
	s_nop 0
	v_addc_co_u32_e32 v3, vcc, 0, v143, vcc
	global_load_dwordx4 v[74:77], v[2:3], off
	s_add_i32 s31, s30, 0x4000
	s_cmpk_lt_i32 s31, 0x4400
	s_cselect_b64 s[2:3], -1, 0
	s_and_b64 s[6:7], s[2:3], exec
	s_cselect_b32 s6, s31, s22
	s_max_i32 s7, s6, 1
	s_add_i32 s23, s7, -1
	s_ashr_i32 s7, s6, 31
	v_add_co_u32_e32 v0, vcc, 0x5f00000, v0
	s_lshl_b64 s[8:9], s[6:7], 10
	s_mul_hi_i32 s33, s6, 0xe00
	s_mul_i32 s34, s6, 0xe00
	v_mad_i64_i32 v[4:5], s[6:7], s6, v152, v[138:139]
	v_mad_u64_u32 v[6:7], s[6:7], s23, v152, v[138:139]
	v_lshl_add_u64 v[2:3], s[16:17], 0, v[176:177]
	v_addc_co_u32_e32 v1, vcc, 0, v1, vcc
	s_add_u32 s6, s92, s34
	global_load_dwordx4 v[56:59], v[2:3], off
	global_load_dwordx4 v[48:51], v[0:1], off offset:2080
	v_lshl_add_u64 v[0:1], v[112:113], 0, s[8:9]
	v_lshl_add_u64 v[2:3], v[114:115], 0, s[8:9]
	s_addc_u32 s7, s93, s33
	global_load_dwordx4 v[40:43], v[0:1], off
	s_nop 0
	global_load_dwordx4 v[0:3], v[2:3], off
	s_nop 0
	global_load_dwordx4 v[20:23], v[4:5], off
	global_load_dwordx4 v[24:27], v[4:5], off offset:1024
	global_load_dwordx4 v[8:11], v[4:5], off offset:2048
	global_load_dwordx4 v[36:39], v[6:7], off
	global_load_dwordx4 v[32:35], v[6:7], off offset:1024
	global_load_dwordx4 v[28:31], v[6:7], off offset:2048
	v_lshl_add_u64 v[6:7], s[6:7], 0, v[140:141]
	v_lshl_add_u64 v[4:5], v[116:117], 0, s[8:9]
	v_add_co_u32_e32 v6, vcc, s27, v6
	global_load_dwordx4 v[16:19], v[4:5], off
	v_lshl_add_u64 v[4:5], v[118:119], 0, s[8:9]
	v_addc_co_u32_e32 v7, vcc, 0, v7, vcc
	global_load_dwordx4 v[12:15], v[4:5], off
	s_nop 0
	global_load_dwordx4 v[4:7], v[6:7], off offset:2080
	s_cmpk_gt_i32 s22, 0x3fff
	s_cselect_b64 s[6:7], -1, 0
	s_cmpk_lt_i32 s22, 0x4000
	s_cselect_b32 s8, 0x7ff, 7
	s_and_b32 s8, s8, s22
	s_cmp_lg_u32 s8, 0
	s_cselect_b64 s[22:23], -1, 0
	s_cmp_eq_u32 s8, 0
	s_waitcnt vmcnt(13)
	v_lshlrev_b32_e32 v82, 16, v74
	v_and_b32_e32 v83, 0xffff0000, v74
	v_add_f32_e32 v74, 0, v82
	v_lshlrev_b32_e32 v80, 16, v76
	v_and_b32_e32 v81, 0xffff0000, v76
	v_lshlrev_b32_e32 v76, 16, v75
	v_add_f32_e32 v74, v74, v83
	v_lshlrev_b32_e32 v78, 16, v77
	v_and_b32_e32 v79, 0xffff0000, v77
	v_and_b32_e32 v77, 0xffff0000, v75
	v_add_f32_e32 v74, v74, v76
	v_add_f32_e32 v74, v74, v77
	v_add_f32_e32 v74, v74, v80
	v_add_f32_e32 v74, v74, v81
	v_add_f32_e32 v74, v74, v78
	v_add_f32_e32 v74, v74, v79
	s_nop 1
	v_add_f32_dpp v74, v74, v74 quad_perm:[1,0,3,2] row_mask:0xf bank_mask:0xf bound_ctrl:1
	s_nop 1
	v_add_f32_dpp v74, v74, v74 quad_perm:[2,3,0,1] row_mask:0xf bank_mask:0xf bound_ctrl:1
	s_nop 1
	v_add_f32_dpp v74, v74, v74 row_half_mirror row_mask:0xf bank_mask:0xf bound_ctrl:1
	v_mul_f32_e32 v74, 0x3c800000, v74
	v_pk_add_f32 v[144:145], v[82:83], v[74:75] op_sel_hi:[1,0] neg_lo:[0,1] neg_hi:[0,1]
	v_pk_add_f32 v[146:147], v[76:77], v[74:75] op_sel_hi:[1,0] neg_lo:[0,1] neg_hi:[0,1]
	v_pk_mul_f32 v[82:83], v[144:145], v[144:145]
	v_pk_mul_f32 v[76:77], v[146:147], v[146:147]
	v_pk_add_f32 v[150:151], v[78:79], v[74:75] op_sel_hi:[1,0] neg_lo:[0,1] neg_hi:[0,1]
	v_add_f32_e32 v78, v82, v83
	v_pk_add_f32 v[148:149], v[80:81], v[74:75] op_sel_hi:[1,0] neg_lo:[0,1] neg_hi:[0,1]
	v_add_f32_e32 v76, v76, v78
	v_pk_mul_f32 v[80:81], v[148:149], v[148:149]
	v_add_f32_e32 v76, v77, v76
	v_add_f32_e32 v76, v80, v76
	v_pk_mul_f32 v[74:75], v[150:151], v[150:151]
	v_add_f32_e32 v76, v81, v76
	v_add_f32_e32 v74, v74, v76
	v_add_f32_e32 v74, v75, v74
	s_nop 1
	v_add_f32_dpp v74, v74, v74 quad_perm:[1,0,3,2] row_mask:0xf bank_mask:0xf bound_ctrl:1
	s_nop 1
	v_add_f32_dpp v156, v74, v74 quad_perm:[2,3,0,1] row_mask:0xf bank_mask:0xf bound_ctrl:1
	s_nop 1
	v_mov_b32_dpp v157, v156 row_half_mirror row_mask:0xf bank_mask:0xf bound_ctrl:1
	s_cbranch_scc1 .LBB0_914
	global_load_dwordx4 v[72:75], v[72:73], off
	s_waitcnt vmcnt(0)
	v_lshlrev_b32_e32 v76, 16, v72
	v_and_b32_e32 v77, 0xffff0000, v72
	v_lshlrev_b32_e32 v78, 16, v73
	v_and_b32_e32 v79, 0xffff0000, v73
	v_lshlrev_b32_e32 v72, 16, v74
	v_and_b32_e32 v73, 0xffff0000, v74
	v_lshlrev_b32_e32 v74, 16, v75
	v_and_b32_e32 v75, 0xffff0000, v75
	v_cndmask_b32_e64 v80, 0, 1, s[6:7]
	v_cmp_ne_u32_e64 s[6:7], 1, v80
	s_cbranch_execz .LBB0_915
	s_branch .LBB0_917
